# stack28 + attention back-edge rotation: step-top counter/exit-test/address bookkeeping moved in front of the previous half's step-end barrier
# speedup vs baseline: 1.0023x; 1.0023x over previous
.Li0_sm:
	ds_read_b64_tr_b16 v[188:189], v158 offset:0x400
	ds_read_b64_tr_b16 v[190:191], v158 offset:0xc00
	ds_read_b64_tr_b16 v[192:193], v158 offset:0x600
	ds_read_b64_tr_b16 v[194:195], v158 offset:0xe00
	s_waitcnt lgkmcnt(6)
	v_mfma_f32_32x32x16_bf16 v[48:63], v[176:179], v[180:183], v[48:63]
	ds_read_b64_tr_b16 v[180:181], v158 offset:0x1000
	ds_read_b64_tr_b16 v[182:183], v158 offset:0x1800
	v_mul_f32_e32 v114, 0xbe0293ee, v166
	v_max_f32_e32 v112, v65, v65
	v_max_f32_e32 v113, v64, v64
	v_fmamk_f32 v64, v64, 0x3e0293ee, v114
	v_max_f32_e32 v112, v113, v112
	v_exp_f32_e32 v64, v64
	s_waitcnt lgkmcnt(6)
	v_mfma_f32_32x32x16_bf16 v[32:47], v[176:179], v[184:187], v[32:47]
	ds_read_b64_tr_b16 v[184:185], v158 offset:0x1200
	ds_read_b64_tr_b16 v[186:187], v158 offset:0x1a00
	v_fmamk_f32 v65, v65, 0x3e0293ee, v114
	v_max3_f32 v112, v112, v66, v67
	v_exp_f32_e32 v65, v65
	v_fmamk_f32 v66, v66, 0x3e0293ee, v114
	v_exp_f32_e32 v66, v66
	s_waitcnt lgkmcnt(6)
	v_mfma_f32_32x32x16_bf16 v[16:31], v[176:179], v[188:191], v[16:31]
	ds_read_b64_tr_b16 v[188:189], v158 offset:0x1400
	ds_read_b64_tr_b16 v[190:191], v158 offset:0x1c00
	v_fmamk_f32 v67, v67, 0x3e0293ee, v114
	v_max3_f32 v112, v112, v68, v69
	v_exp_f32_e32 v67, v67
	v_fmamk_f32 v68, v68, 0x3e0293ee, v114
	v_add_f32_e32 v115, 0, v64
	s_waitcnt lgkmcnt(6)
	v_mfma_f32_32x32x16_bf16 v[0:15], v[176:179], v[192:195], v[0:15]
	ds_read_b64_tr_b16 v[192:193], v158 offset:0x1600
	ds_read_b64_tr_b16 v[194:195], v158 offset:0x1e00
	v_exp_f32_e32 v68, v68
	v_fmamk_f32 v69, v69, 0x3e0293ee, v114
	v_max3_f32 v112, v112, v70, v71
	v_add_f32_e32 v115, v65, v115
	v_exp_f32_e32 v69, v69
	s_waitcnt lgkmcnt(6)
	v_mfma_f32_32x32x16_bf16 v[48:63], v[124:127], v[180:183], v[48:63]
	ds_read_b64_tr_b16 v[180:181], v158 offset:0x2000
	ds_read_b64_tr_b16 v[182:183], v158 offset:0x2800
	v_fmamk_f32 v70, v70, 0x3e0293ee, v114
	v_add_f32_e32 v115, v66, v115
	v_exp_f32_e32 v70, v70
	v_fmamk_f32 v71, v71, 0x3e0293ee, v114
	v_max3_f32 v112, v112, v72, v73
	s_waitcnt lgkmcnt(6)
	v_mfma_f32_32x32x16_bf16 v[32:47], v[124:127], v[184:187], v[32:47]
	ds_read_b64_tr_b16 v[184:185], v158 offset:0x2200
	ds_read_b64_tr_b16 v[186:187], v158 offset:0x2a00
	v_add_f32_e32 v115, v67, v115
	v_exp_f32_e32 v71, v71
	v_fmamk_f32 v72, v72, 0x3e0293ee, v114
	v_add_f32_e32 v115, v68, v115
	v_exp_f32_e32 v72, v72
	s_waitcnt lgkmcnt(6)
	v_mfma_f32_32x32x16_bf16 v[16:31], v[124:127], v[188:191], v[16:31]
	ds_read_b64_tr_b16 v[188:189], v158 offset:0x2400
	ds_read_b64_tr_b16 v[190:191], v158 offset:0x2c00
	v_fmamk_f32 v73, v73, 0x3e0293ee, v114
	v_max3_f32 v112, v112, v74, v75
	v_add_f32_e32 v115, v69, v115
	v_exp_f32_e32 v73, v73
	v_fmamk_f32 v74, v74, 0x3e0293ee, v114
	s_waitcnt lgkmcnt(6)
	v_mfma_f32_32x32x16_bf16 v[0:15], v[124:127], v[192:195], v[0:15]
	ds_read_b64_tr_b16 v[192:193], v158 offset:0x2600
	ds_read_b64_tr_b16 v[194:195], v158 offset:0x2e00
	v_add_f32_e32 v115, v70, v115
	v_exp_f32_e32 v74, v74
	v_fmamk_f32 v75, v75, 0x3e0293ee, v114
	v_max3_f32 v112, v112, v76, v77
	v_add_f32_e32 v115, v71, v115
	s_waitcnt lgkmcnt(6)
	v_mfma_f32_32x32x16_bf16 v[48:63], v[172:175], v[180:183], v[48:63]
	ds_read_b64_tr_b16 v[180:181], v158 offset:0x3000
	ds_read_b64_tr_b16 v[182:183], v158 offset:0x3800
	v_exp_f32_e32 v75, v75
	v_fmamk_f32 v76, v76, 0x3e0293ee, v114
	v_add_f32_e32 v115, v72, v115
	v_exp_f32_e32 v76, v76
	v_fmamk_f32 v77, v77, 0x3e0293ee, v114
	s_waitcnt lgkmcnt(6)
	v_mfma_f32_32x32x16_bf16 v[32:47], v[172:175], v[184:187], v[32:47]
	ds_read_b64_tr_b16 v[184:185], v158 offset:0x3200
	ds_read_b64_tr_b16 v[186:187], v158 offset:0x3a00
	v_max3_f32 v112, v112, v78, v79
	v_add_f32_e32 v115, v73, v115
	v_exp_f32_e32 v77, v77
	v_fmamk_f32 v78, v78, 0x3e0293ee, v114
	v_add_f32_e32 v115, v74, v115
	s_waitcnt lgkmcnt(6)
	v_mfma_f32_32x32x16_bf16 v[16:31], v[172:175], v[188:191], v[16:31]
	ds_read_b64_tr_b16 v[188:189], v158 offset:0x3400
	ds_read_b64_tr_b16 v[190:191], v158 offset:0x3c00
	v_exp_f32_e32 v78, v78
	v_fmac_f32_e32 v114, 0x3e0293ee, v79
	v_add_f32_e32 v115, v75, v115
	v_exp_f32_e32 v79, v114
	v_add_f32_e32 v114, v76, v115
	s_waitcnt lgkmcnt(6)
	v_mfma_f32_32x32x16_bf16 v[0:15], v[172:175], v[192:195], v[0:15]
	ds_read_b64_tr_b16 v[192:193], v158 offset:0x3600
	ds_read_b64_tr_b16 v[194:195], v158 offset:0x3e00
	v_mov_b32_e32 v113, v112
	v_add_f32_e32 v114, v77, v114
	s_nop 0
	v_permlane32_swap_b32_e32 v112, v113
	v_add_f32_e32 v114, v78, v114
	v_add_f32_e32 v120, v79, v114
	v_max_f32_e32 v113, v113, v113
	s_waitcnt lgkmcnt(6)
	v_mfma_f32_32x32x16_bf16 v[48:63], v[168:171], v[180:183], v[48:63]
	v_max_f32_e32 v112, v112, v112
	v_max_f32_e32 v164, v112, v113
	v_mov_b32_e32 v121, v120
	v_cvt_pk_bf16_f32 v112, v64, v65
	v_cvt_pk_bf16_f32 v113, v66, v67
	v_cvt_pk_bf16_f32 v114, v68, v69
	v_cvt_pk_bf16_f32 v115, v70, v71
	s_waitcnt lgkmcnt(4)
	v_mfma_f32_32x32x16_bf16 v[32:47], v[168:171], v[184:187], v[32:47]
	v_cvt_pk_bf16_f32 v116, v72, v73
	v_cvt_pk_bf16_f32 v117, v74, v75
	v_cvt_pk_bf16_f32 v118, v76, v77
	v_cvt_pk_bf16_f32 v119, v78, v79
	s_nop 1
	v_permlane32_swap_b32_e32 v120, v121
	v_permlane32_swap_b32_e32 v112, v114
	s_waitcnt lgkmcnt(2)
	v_mfma_f32_32x32x16_bf16 v[16:31], v[168:171], v[188:191], v[16:31]
	v_permlane32_swap_b32_e32 v113, v115
	v_permlane32_swap_b32_e32 v116, v118
	v_permlane32_swap_b32_e32 v117, v119
	ds_write_b128 v157, v[112:115] offset:4096
	ds_write_b128 v157, v[116:119] offset:5120
	v_add_f32_e32 v120, v120, v121
	v_add_f32_e32 v155, v155, v120
	s_waitcnt lgkmcnt(2)
	v_mfma_f32_32x32x16_bf16 v[0:15], v[168:171], v[192:195], v[0:15]
	s_and_saveexec_b64 s[52:53], s[4:5]
	ds_write_b32 v160, v164 offset:8448
	s_or_b64 exec, exec, s[52:53]
	s_cmp_gt_i32 s19, s18
	s_cselect_b64 s[52:53], -1, 0
	s_cmp_le_i32 s19, s18
	s_cselect_b64 s[54:55], -1, 0
	s_waitcnt vmcnt(0) lgkmcnt(0)
	s_barrier
	ds_read_b128 v[124:127], v128 offset:5120
	ds_read_b128 v[120:123], v128 offset:4096
	ds_read_b32 v128, v156 offset:8448
	s_and_b64 vcc, exec, s[52:53]
	s_cbranch_vccnz .LBB0_752
	s_branch .Li1_entry

.Li1_sm:
	ds_read_b64_tr_b16 v[188:189], v158 offset:0x8400
	ds_read_b64_tr_b16 v[190:191], v158 offset:0x8c00
	ds_read_b64_tr_b16 v[192:193], v158 offset:0x8600
	ds_read_b64_tr_b16 v[194:195], v158 offset:0x8e00
	s_waitcnt lgkmcnt(6)
	v_mfma_f32_32x32x16_bf16 v[48:63], v[176:179], v[180:183], v[48:63]
	ds_read_b64_tr_b16 v[180:181], v158 offset:0x9000
	ds_read_b64_tr_b16 v[182:183], v158 offset:0x9800
	v_mul_f32_e32 v114, 0xbe0293ee, v165
	v_max_f32_e32 v112, v65, v65
	v_max_f32_e32 v113, v64, v64
	v_fmamk_f32 v64, v64, 0x3e0293ee, v114
	v_max_f32_e32 v112, v113, v112
	v_exp_f32_e32 v64, v64
	s_waitcnt lgkmcnt(6)
	v_mfma_f32_32x32x16_bf16 v[32:47], v[176:179], v[184:187], v[32:47]
	ds_read_b64_tr_b16 v[184:185], v158 offset:0x9200
	ds_read_b64_tr_b16 v[186:187], v158 offset:0x9a00
	v_fmamk_f32 v65, v65, 0x3e0293ee, v114
	v_max3_f32 v112, v112, v66, v67
	v_exp_f32_e32 v65, v65
	v_fmamk_f32 v66, v66, 0x3e0293ee, v114
	v_exp_f32_e32 v66, v66
	s_waitcnt lgkmcnt(6)
	v_mfma_f32_32x32x16_bf16 v[16:31], v[176:179], v[188:191], v[16:31]
	ds_read_b64_tr_b16 v[188:189], v158 offset:0x9400
	ds_read_b64_tr_b16 v[190:191], v158 offset:0x9c00
	v_fmamk_f32 v67, v67, 0x3e0293ee, v114
	v_max3_f32 v112, v112, v68, v69
	v_exp_f32_e32 v67, v67
	v_fmamk_f32 v68, v68, 0x3e0293ee, v114
	v_add_f32_e32 v115, 0, v64
	s_waitcnt lgkmcnt(6)
	v_mfma_f32_32x32x16_bf16 v[0:15], v[176:179], v[192:195], v[0:15]
	ds_read_b64_tr_b16 v[192:193], v158 offset:0x9600
	ds_read_b64_tr_b16 v[194:195], v158 offset:0x9e00
	v_exp_f32_e32 v68, v68
	v_fmamk_f32 v69, v69, 0x3e0293ee, v114
	v_max3_f32 v112, v112, v70, v71
	v_add_f32_e32 v115, v65, v115
	v_exp_f32_e32 v69, v69
	s_waitcnt lgkmcnt(6)
	v_mfma_f32_32x32x16_bf16 v[48:63], v[168:171], v[180:183], v[48:63]
	ds_read_b64_tr_b16 v[180:181], v158 offset:0xa000
	ds_read_b64_tr_b16 v[182:183], v158 offset:0xa800
	v_fmamk_f32 v70, v70, 0x3e0293ee, v114
	v_add_f32_e32 v115, v66, v115
	v_exp_f32_e32 v70, v70
	v_fmamk_f32 v71, v71, 0x3e0293ee, v114
	v_max3_f32 v112, v112, v72, v73
	s_waitcnt lgkmcnt(6)
	v_mfma_f32_32x32x16_bf16 v[32:47], v[168:171], v[184:187], v[32:47]
	ds_read_b64_tr_b16 v[184:185], v158 offset:0xa200
	ds_read_b64_tr_b16 v[186:187], v158 offset:0xaa00
	v_add_f32_e32 v115, v67, v115
	v_exp_f32_e32 v71, v71
	v_fmamk_f32 v72, v72, 0x3e0293ee, v114
	v_add_f32_e32 v115, v68, v115
	v_exp_f32_e32 v72, v72
	s_waitcnt lgkmcnt(6)
	v_mfma_f32_32x32x16_bf16 v[16:31], v[168:171], v[188:191], v[16:31]
	ds_read_b64_tr_b16 v[188:189], v158 offset:0xa400
	ds_read_b64_tr_b16 v[190:191], v158 offset:0xac00
	v_fmamk_f32 v73, v73, 0x3e0293ee, v114
	v_max3_f32 v112, v112, v74, v75
	v_add_f32_e32 v115, v69, v115
	v_exp_f32_e32 v73, v73
	v_fmamk_f32 v74, v74, 0x3e0293ee, v114
	s_waitcnt lgkmcnt(6)
	v_mfma_f32_32x32x16_bf16 v[0:15], v[168:171], v[192:195], v[0:15]
	ds_read_b64_tr_b16 v[192:193], v158 offset:0xa600
	ds_read_b64_tr_b16 v[194:195], v158 offset:0xae00
	v_add_f32_e32 v115, v70, v115
	v_exp_f32_e32 v74, v74
	v_fmamk_f32 v75, v75, 0x3e0293ee, v114
	v_max3_f32 v112, v112, v76, v77
	v_add_f32_e32 v115, v71, v115
	s_waitcnt lgkmcnt(6)
	v_mfma_f32_32x32x16_bf16 v[48:63], v[172:175], v[180:183], v[48:63]
	ds_read_b64_tr_b16 v[180:181], v158 offset:0xb000
	ds_read_b64_tr_b16 v[182:183], v158 offset:0xb800
	v_exp_f32_e32 v75, v75
	v_fmamk_f32 v76, v76, 0x3e0293ee, v114
	v_add_f32_e32 v115, v72, v115
	v_exp_f32_e32 v76, v76
	v_fmamk_f32 v77, v77, 0x3e0293ee, v114
	s_waitcnt lgkmcnt(6)
	v_mfma_f32_32x32x16_bf16 v[32:47], v[172:175], v[184:187], v[32:47]
	ds_read_b64_tr_b16 v[184:185], v158 offset:0xb200
	ds_read_b64_tr_b16 v[186:187], v158 offset:0xba00
	v_max3_f32 v112, v112, v78, v79
	v_add_f32_e32 v115, v73, v115
	v_exp_f32_e32 v77, v77
	v_fmamk_f32 v78, v78, 0x3e0293ee, v114
	v_add_f32_e32 v115, v74, v115
	s_waitcnt lgkmcnt(6)
	v_mfma_f32_32x32x16_bf16 v[16:31], v[172:175], v[188:191], v[16:31]
	ds_read_b64_tr_b16 v[188:189], v158 offset:0xb400
	ds_read_b64_tr_b16 v[190:191], v158 offset:0xbc00
	v_exp_f32_e32 v78, v78
	v_fmac_f32_e32 v114, 0x3e0293ee, v79
	v_add_f32_e32 v115, v75, v115
	v_exp_f32_e32 v79, v114
	v_add_f32_e32 v114, v76, v115
	s_waitcnt lgkmcnt(6)
	v_mfma_f32_32x32x16_bf16 v[0:15], v[172:175], v[192:195], v[0:15]
	ds_read_b64_tr_b16 v[192:193], v158 offset:0xb600
	ds_read_b64_tr_b16 v[194:195], v158 offset:0xbe00
	v_mov_b32_e32 v113, v112
	v_add_f32_e32 v114, v77, v114
	s_nop 0
	v_permlane32_swap_b32_e32 v112, v113
	v_add_f32_e32 v114, v78, v114
	v_add_f32_e32 v120, v79, v114
	v_max_f32_e32 v113, v113, v113
	s_waitcnt lgkmcnt(6)
	v_mfma_f32_32x32x16_bf16 v[48:63], v[124:127], v[180:183], v[48:63]
	v_max_f32_e32 v112, v112, v112
	v_max_f32_e32 v164, v112, v113
	v_mov_b32_e32 v121, v120
	v_cvt_pk_bf16_f32 v112, v64, v65
	v_cvt_pk_bf16_f32 v113, v66, v67
	v_cvt_pk_bf16_f32 v114, v68, v69
	v_cvt_pk_bf16_f32 v115, v70, v71
	s_waitcnt lgkmcnt(4)
	v_mfma_f32_32x32x16_bf16 v[32:47], v[124:127], v[184:187], v[32:47]
	v_cvt_pk_bf16_f32 v116, v72, v73
	v_cvt_pk_bf16_f32 v117, v74, v75
	v_cvt_pk_bf16_f32 v118, v76, v77
	v_cvt_pk_bf16_f32 v119, v78, v79
	s_nop 1
	v_permlane32_swap_b32_e32 v120, v121
	v_permlane32_swap_b32_e32 v112, v114
	s_waitcnt lgkmcnt(2)
	v_mfma_f32_32x32x16_bf16 v[16:31], v[124:127], v[188:191], v[16:31]
	v_permlane32_swap_b32_e32 v113, v115
	v_permlane32_swap_b32_e32 v116, v118
	v_permlane32_swap_b32_e32 v117, v119
	ds_write_b128 v157, v[112:115]
	ds_write_b128 v157, v[116:119] offset:1024
	v_add_f32_e32 v120, v120, v121
	v_add_f32_e32 v155, v155, v120
	s_waitcnt lgkmcnt(2)
	v_mfma_f32_32x32x16_bf16 v[0:15], v[124:127], v[192:195], v[0:15]
	s_and_saveexec_b64 s[54:55], s[4:5]
	ds_write_b32 v160, v164 offset:8192
	s_or_b64 exec, exec, s[54:55]
	s_add_u32 s50, s50, 0x8000
	s_addc_u32 s51, s51, 0
	s_add_i32 s19, s19, 2
	v_add_u32_e32 v162, 0xffffff80, v162
	s_addk_i32 s83, 0x80
	s_and_b64 vcc, exec, s[52:53]
	s_cbranch_vccnz .Li1_exit
	v_add_u32_e32 v128, s78, v145
	s_add_i32 s54, s19, -2
	s_cmp_lt_i32 s54, s18
	s_cselect_b64 s[52:53], -1, 0
	v_lshl_add_u64 v[134:135], s[50:51], 0, v[132:133]
	s_waitcnt vmcnt(0) lgkmcnt(0)
	s_barrier
	ds_read_b128 v[124:127], v128 offset:1024
	ds_read_b128 v[120:123], v128
	ds_read_b32 v166, v156 offset:8192
	s_cmp_ge_i32 s54, s18
	s_cbranch_scc1 .LBB0_738
	s_branch .Li0_entry
.Li1_exit:
	s_waitcnt vmcnt(0) lgkmcnt(0)
	s_barrier
	s_branch .LBB0_762
